# v15 + 48 bytes of s_nop after each of the four norm loops: every later code address keeps its v11 offset modulo 64 (placement control for the norm change)
# speedup vs baseline: 1.0016x; 1.0016x over previous
; template <bool COMBINE, bool SRC_F32>
; __device__ __forceinline__ void norm_phase(LAS unsigned char* lds, const void* src_lat, const void* src_ctx, _Float16* xw_ctx, const float* part, int nrows, const float* g, const float* modl, int shift_idx, int scale_idx, bf16* HN, int tid, int lane, int wave) {
;     ...
;     __syncthreads();
.LBB0_472:
	s_waitcnt lgkmcnt(0)
	s_barrier
	s_nop 0
	s_nop 0
	s_nop 0
	s_nop 0
	s_nop 0
	s_nop 0
	s_nop 0
	s_nop 0
	s_nop 0
	s_nop 0
	s_nop 0
	s_nop 0
